# counted vmcnt waits for yo partner-row loads at SSD y-out (do not drain next-chunk staging loads)
# speedup vs baseline: 1.0045x; 1.0036x over previous
.LBB0_1106:
	s_waitcnt lgkmcnt(0)
	v_mul_f32_e32 v82, 0x3fb8aa3b, v165
	v_exp_f32_e32 v86, v82
	s_andn2_b64 vcc, exec, s[22:23]
	v_pk_fma_f32 v[66:67], v[66:67], v[86:87], v[110:111] op_sel_hi:[1,0,1]
	v_pk_fma_f32 v[82:83], v[68:69], v[86:87], v[112:113] op_sel_hi:[1,0,1]
	v_pk_fma_f32 v[70:71], v[70:71], v[86:87], v[106:107] op_sel_hi:[1,0,1]
	v_pk_fma_f32 v[84:85], v[72:73], v[86:87], v[108:109] op_sel_hi:[1,0,1]
	v_pk_fma_f32 v[68:69], v[78:79], v[86:87], v[102:103] op_sel_hi:[1,0,1]
	v_pk_fma_f32 v[78:79], v[80:81], v[86:87], v[104:105] op_sel_hi:[1,0,1]
	v_pk_fma_f32 v[72:73], v[74:75], v[86:87], v[98:99] op_sel_hi:[1,0,1]
	v_pk_fma_f32 v[74:75], v[76:77], v[86:87], v[100:101] op_sel_hi:[1,0,1]
	s_cbranch_vccnz .LBB0_1108
	s_cmp_eq_u32 s47, 33
	s_cbranch_scc1 .Lmy_yoL1_a
	s_waitcnt vmcnt(11)
	s_branch .Lmy_yo1_a

.Lmy_yo1_a:
	v_and_b32_e32 v77, 0xffff0000, v60
	v_lshlrev_b32_e32 v76, 16, v60
	v_and_b32_e32 v81, 0xffff0000, v61
	v_lshlrev_b32_e32 v80, 16, v61
	v_and_b32_e32 v61, 0xffff0000, v62
	v_lshlrev_b32_e32 v60, 16, v62
	v_and_b32_e32 v87, 0xffff0000, v63
	v_lshlrev_b32_e32 v86, 16, v63
	s_cmp_eq_u32 s47, 33
	s_cbranch_scc1 .Lmy_yoL2_a
	s_waitcnt vmcnt(10)
	s_branch .Lmy_yo2_a

.Lmy_yo2_a:
	v_and_b32_e32 v63, 0xffff0000, v56
	v_lshlrev_b32_e32 v62, 16, v56
	v_and_b32_e32 v89, 0xffff0000, v57
	v_lshlrev_b32_e32 v88, 16, v57
	v_and_b32_e32 v57, 0xffff0000, v58
	v_lshlrev_b32_e32 v56, 16, v58
	v_and_b32_e32 v91, 0xffff0000, v59
	v_lshlrev_b32_e32 v90, 16, v59
	v_pk_add_f32 v[66:67], v[66:67], v[76:77]
	v_pk_add_f32 v[82:83], v[82:83], v[80:81]
	v_pk_add_f32 v[70:71], v[70:71], v[60:61]
	v_pk_add_f32 v[84:85], v[84:85], v[86:87]
	v_pk_add_f32 v[68:69], v[68:69], v[62:63]
	v_pk_add_f32 v[78:79], v[78:79], v[88:89]
	v_pk_add_f32 v[72:73], v[72:73], v[56:57]
	v_pk_add_f32 v[74:75], v[74:75], v[90:91]

.LBB0_1228:
	s_waitcnt lgkmcnt(0)
	v_mul_f32_e32 v82, 0x3fb8aa3b, v166
	v_exp_f32_e32 v86, v82
	ds_read2_b64 v[82:85], v162 offset1:4
	s_andn2_b64 vcc, exec, s[36:37]
	v_pk_fma_f32 v[78:79], v[78:79], v[86:87], v[110:111] op_sel_hi:[1,0,1]
	v_pk_fma_f32 v[74:75], v[74:75], v[86:87], v[106:107] op_sel_hi:[1,0,1]
	s_waitcnt lgkmcnt(0)
	v_and_b32_e32 v89, 0xffff0000, v82
	v_lshlrev_b32_e32 v88, 16, v82
	v_pk_fma_f32 v[78:79], v[130:131], v[88:89], v[78:79]
	v_and_b32_e32 v89, 0xffff0000, v83
	v_lshlrev_b32_e32 v88, 16, v83
	v_and_b32_e32 v83, 0xffff0000, v84
	v_lshlrev_b32_e32 v82, 16, v84
	v_pk_fma_f32 v[74:75], v[130:131], v[82:83], v[74:75]
	v_pk_fma_f32 v[76:77], v[76:77], v[86:87], v[108:109] op_sel_hi:[1,0,1]
	v_and_b32_e32 v83, 0xffff0000, v85
	v_lshlrev_b32_e32 v82, 16, v85
	v_pk_fma_f32 v[76:77], v[130:131], v[82:83], v[76:77]
	ds_read2_b64 v[82:85], v162 offset0:8 offset1:12
	v_pk_fma_f32 v[80:81], v[80:81], v[86:87], v[112:113] op_sel_hi:[1,0,1]
	v_pk_fma_f32 v[70:71], v[70:71], v[86:87], v[102:103] op_sel_hi:[1,0,1]
	v_pk_fma_f32 v[80:81], v[130:131], v[88:89], v[80:81]
	v_pk_fma_f32 v[66:67], v[66:67], v[86:87], v[98:99] op_sel_hi:[1,0,1]
	s_waitcnt lgkmcnt(0)
	v_and_b32_e32 v89, 0xffff0000, v82
	v_lshlrev_b32_e32 v88, 16, v82
	v_pk_fma_f32 v[70:71], v[130:131], v[88:89], v[70:71]
	v_and_b32_e32 v89, 0xffff0000, v83
	v_lshlrev_b32_e32 v88, 16, v83
	v_and_b32_e32 v83, 0xffff0000, v84
	v_lshlrev_b32_e32 v82, 16, v84
	v_pk_fma_f32 v[72:73], v[72:73], v[86:87], v[104:105] op_sel_hi:[1,0,1]
	v_pk_fma_f32 v[66:67], v[130:131], v[82:83], v[66:67]
	v_pk_fma_f32 v[68:69], v[68:69], v[86:87], v[100:101] op_sel_hi:[1,0,1]
	v_and_b32_e32 v83, 0xffff0000, v85
	v_lshlrev_b32_e32 v82, 16, v85
	v_pk_fma_f32 v[72:73], v[130:131], v[88:89], v[72:73]
	v_pk_fma_f32 v[68:69], v[130:131], v[82:83], v[68:69]
	s_cbranch_vccnz .LBB0_1230
	s_cmp_eq_u32 s34, 33
	s_cbranch_scc1 .Lmy_yoL1_b
	s_waitcnt vmcnt(11)
	s_branch .Lmy_yo1_b

.Lmy_yo1_b:
	v_and_b32_e32 v83, 0xffff0000, v60
	v_lshlrev_b32_e32 v82, 16, v60
	v_and_b32_e32 v85, 0xffff0000, v61
	v_lshlrev_b32_e32 v84, 16, v61
	v_and_b32_e32 v61, 0xffff0000, v62
	v_lshlrev_b32_e32 v60, 16, v62
	v_and_b32_e32 v87, 0xffff0000, v63
	v_lshlrev_b32_e32 v86, 16, v63
	s_cmp_eq_u32 s34, 33
	s_cbranch_scc1 .Lmy_yoL2_b
	s_waitcnt vmcnt(10)
	s_branch .Lmy_yo2_b

.Lmy_yo2_b:
	v_and_b32_e32 v63, 0xffff0000, v56
	v_lshlrev_b32_e32 v62, 16, v56
	v_and_b32_e32 v89, 0xffff0000, v57
	v_lshlrev_b32_e32 v88, 16, v57
	v_and_b32_e32 v57, 0xffff0000, v58
	v_lshlrev_b32_e32 v56, 16, v58
	v_and_b32_e32 v91, 0xffff0000, v59
	v_lshlrev_b32_e32 v90, 16, v59
	v_pk_add_f32 v[78:79], v[78:79], v[82:83]
	v_pk_add_f32 v[80:81], v[80:81], v[84:85]
	v_pk_add_f32 v[74:75], v[74:75], v[60:61]
	v_pk_add_f32 v[76:77], v[76:77], v[86:87]
	v_pk_add_f32 v[70:71], v[70:71], v[62:63]
	v_pk_add_f32 v[72:73], v[72:73], v[88:89]
	v_pk_add_f32 v[66:67], v[66:67], v[56:57]
	v_pk_add_f32 v[68:69], v[68:69], v[90:91]
